# code placement: whole instruction stream shifted by 4 bytes (one s_nop at kernel entry)
# baseline (speedup 1.0000x reference)
_Z10fwd_kernel6Params:
	s_nop 0
	s_load_dwordx8 s[88:95], s[0:1], 0xa0
	s_load_dwordx8 s[4:11], s[0:1], 0x80
	s_mov_b32 s70, s2
	v_and_b32_e32 v197, 0x3ff, v0
	s_waitcnt lgkmcnt(0)
	v_writelane_b32 v252, s4, 0
	s_nop 1
	v_writelane_b32 v252, s5, 1
	v_writelane_b32 v252, s6, 2
	v_writelane_b32 v252, s7, 3
	v_writelane_b32 v252, s8, 4
	v_writelane_b32 v252, s9, 5
	v_writelane_b32 v252, s10, 6
	v_writelane_b32 v252, s11, 7
	v_cmp_eq_u32_e64 s[4:5], 0, v197
	s_mov_b64 s[6:7], exec
	s_nop 0
	v_writelane_b32 v252, s4, 8
	s_nop 1
	v_writelane_b32 v252, s5, 9
	s_and_b64 s[4:5], s[6:7], s[4:5]
	s_mov_b64 exec, s[4:5]
	s_cbranch_execz .LBB0_2
	s_add_i32 s4, 0, 0x20000
	v_mov_b32_e32 v1, 0
	v_mov_b32_e32 v2, s4
	s_add_i32 s4, 0, 0x20004
	ds_write_b32 v2, v1
	v_mov_b32_e32 v2, s4
	ds_write_b32 v2, v1
